# ffn-up epilogue: lane-permuted (ds_bpermute) stores so each 4-lane quad writes 64 contiguous bytes of one row
# baseline (speedup 1.0000x reference)
.LBB0_95:
	s_mov_b32 s5, -1
	s_getreg_b32 s6, hwreg(HW_REG_HW_ID, 0, 6)
	s_and_b32 s6, s6, 63
	s_lshl_b32 s6, s6, 2
	s_add_i32 s6, s6, 0
	s_add_i32 s6, s6, 0x20200
	v_mov_b32_e32 v140, s6
	ds_read_b32 v140, v140
	v_mbcnt_lo_u32_b32 v142, s5, 0
	v_mbcnt_hi_u32_b32 v142, s5, v142
	v_bfrev_b32_e32 v144, 0.5
	s_mov_b64 s[8:9], -1
	s_waitcnt lgkmcnt(0)
	v_readfirstlane_b32 s5, v140
	s_nop 1
	v_lshl_add_u32 v142, s5, 6, v142
	v_and_b32_e32 v184, 63, v142
	v_and_b32_e32 v185, 3, v184
	v_lshrrev_b32_e32 v186, 2, v184
	v_and_b32_e32 v187, 60, v184
	v_lshl_or_b32 v169, v185, 6, v187
	v_and_b32_e32 v187, 15, v184
	v_lshrrev_b32_e32 v184, 4, v184
	v_sub_u32_e32 v186, v186, v187
	v_sub_u32_e32 v185, v185, v184
	v_lshlrev_b32_e32 v186, 7, v186
	v_lshl_add_u32 v170, v185, 4, v186
	v_ashrrev_i32_e32 v171, 31, v170
	s_lshl_b32 s5, s46, 8
	v_readfirstlane_b32 s10, v142
	s_ashr_i32 s6, s10, 2
	s_andn2_b32 s6, s6, 63
	v_bfe_u32 v140, v142, 4, 2
	s_cmp_gt_u32 s94, 3
	v_and_or_b32 v158, v142, 15, s6
	v_lshlrev_b32_e32 v143, 2, v140
	v_lshlrev_b32_e32 v142, 2, v142
	s_cselect_b64 s[6:7], -1, 0
	v_add_u32_e32 v162, s5, v158
	v_bitop3_b32 v168, v142, 64, v144 bitop3:0x6c
	v_bitop3_b32 v167, v142, s84, v144 bitop3:0x6c
	s_and_b64 vcc, exec, s[6:7]
	v_lshlrev_b32_e32 v160, 2, v143
	s_cbranch_vccz .LBB0_97
	v_ashrrev_i32_e32 v163, 31, v162
	v_lshlrev_b64 v[142:143], 6, v[162:163]
	v_lshl_add_u64 v[142:143], s[44:45], 0, v[142:143]
	v_mov_b32_e32 v161, v141
	v_lshl_add_u64 v[142:143], v[142:143], 0, v[160:161]
	flat_load_dwordx4 v[142:145], v[142:143]
	s_mov_b64 s[8:9], 0
	s_waitcnt vmcnt(0) lgkmcnt(0)
	v_mov_b32_e32 v146, v143
	v_mov_b32_e32 v147, v144
	v_mov_b32_e32 v143, v145
	v_pk_add_f32 v[142:143], v[146:147], v[142:143]
	s_nop 0
	v_add_f32_e32 v142, v142, v143
	ds_bpermute_b32 v143, v168, v142
	s_waitcnt lgkmcnt(0)
	v_add_f32_e32 v142, v142, v143
	ds_bpermute_b32 v143, v167, v142
	s_waitcnt lgkmcnt(0)
	v_add_f32_e32 v142, v142, v143
	v_fmamk_f32 v142, v142, 0x3a800000, v250
	v_rsq_f32_e32 v164, v142

.LBB0_99:
	s_lshr_b32 s8, s10, 1
	s_lshl_b32 s4, s4, 8
	s_and_b32 s9, s8, 64
	v_lshlrev_b32_e32 v140, 3, v140
	s_or_b32 s4, s9, s4
	v_and_or_b32 v140, s8, 32, v140
	s_lshl_b32 s8, s46, 6
	s_ashr_i32 s4, s4, 6
	s_waitcnt lgkmcnt(0)
	v_pk_mul_f32 v[122:123], v[122:123], v[164:165] op_sel_hi:[1,0]
	v_pk_mul_f32 v[120:121], v[120:121], v[164:165] op_sel_hi:[1,0]
	s_add_i32 s8, s4, s8
	v_pk_mul_f32 v[126:127], v[126:127], v[164:165] op_sel_hi:[1,0]
	v_pk_mul_f32 v[124:125], v[124:125], v[164:165] op_sel_hi:[1,0]
	v_max_f32_e32 v120, 0, v120
	v_max_f32_e32 v121, 0, v121
	v_max_f32_e32 v122, 0, v122
	s_ashr_i32 s9, s8, 31
	v_max_f32_e32 v124, 0, v124
	v_mul_f32_e32 v142, v120, v120
	v_max_f32_e32 v120, 0, v125
	v_mul_f32_e32 v125, v121, v121
	v_max_f32_e32 v121, 0, v126
	v_mul_f32_e32 v126, v122, v122
	v_max_f32_e32 v122, 0, v127
	s_lshl_b64 s[10:11], s[8:9], 15
	v_mul_f32_e32 v124, v124, v124
	v_mul_f32_e32 v120, v120, v120
	v_mul_f32_e32 v121, v121, v121
	v_max_f32_e32 v123, 0, v123
	v_mul_f32_e32 v122, v122, v122
	v_ashrrev_i32_e32 v159, 31, v158
	s_add_u32 s58, s86, s10
	v_mul_f32_e32 v123, v123, v123
	v_cvt_pk_bf16_f32 v120, v124, v120
	v_cvt_pk_bf16_f32 v121, v121, v122
	v_cvt_pk_bf16_f32 v122, v142, v125
	s_addc_u32 s59, s87, s11
	v_lshlrev_b64 v[124:125], 7, v[158:159]
	s_or_b32 s8, s8, 2
	v_cvt_pk_bf16_f32 v123, v126, v123
	v_lshl_add_u64 v[126:127], s[58:59], 0, v[124:125]
	v_lshlrev_b32_e32 v140, 1, v140
	v_pk_mul_f32 v[114:115], v[114:115], v[164:165] op_sel_hi:[1,0]
	v_pk_mul_f32 v[112:113], v[112:113], v[164:165] op_sel_hi:[1,0]
	s_ashr_i32 s9, s8, 31
	v_lshl_add_u64 v[126:127], v[126:127], 0, v[140:141]
	v_pk_mul_f32 v[118:119], v[118:119], v[164:165] op_sel_hi:[1,0]
	v_pk_mul_f32 v[116:117], v[116:117], v[164:165] op_sel_hi:[1,0]
	v_max_f32_e32 v112, 0, v112
	v_max_f32_e32 v113, 0, v113
	v_max_f32_e32 v114, 0, v114
	s_lshl_b64 s[8:9], s[8:9], 15
	ds_bpermute_b32 v172, v169, v120
	ds_bpermute_b32 v173, v169, v121
	ds_bpermute_b32 v174, v169, v122
	ds_bpermute_b32 v175, v169, v123
	v_lshl_add_u64 v[176:177], v[126:127], 0, v[170:171]
	v_max_f32_e32 v116, 0, v116
	s_add_u32 s74, s86, s8
	v_mul_f32_e32 v120, v112, v112
	v_max_f32_e32 v112, 0, v117
	v_mul_f32_e32 v117, v113, v113
	v_max_f32_e32 v113, 0, v118
	v_mul_f32_e32 v118, v114, v114
	v_max_f32_e32 v114, 0, v119
	v_mul_f32_e32 v116, v116, v116
	v_mul_f32_e32 v112, v112, v112
	v_mul_f32_e32 v113, v113, v113
	v_mul_f32_e32 v114, v114, v114
	s_addc_u32 s75, s87, s9
	v_max_f32_e32 v115, 0, v115
	v_cvt_pk_bf16_f32 v112, v116, v112
	v_cvt_pk_bf16_f32 v113, v113, v114
	v_cvt_pk_bf16_f32 v114, v120, v117
	v_lshl_add_u64 v[116:117], s[74:75], 0, v[124:125]
	v_mul_f32_e32 v115, v115, v115
	v_lshl_add_u64 v[116:117], v[116:117], 0, v[140:141]
	v_cvt_pk_bf16_f32 v115, v118, v115
	s_waitcnt lgkmcnt(0)
	global_store_dwordx4 v[176:177], v[172:175], off nt
	ds_bpermute_b32 v178, v169, v112
	ds_bpermute_b32 v179, v169, v113
	ds_bpermute_b32 v180, v169, v114
	ds_bpermute_b32 v181, v169, v115
	v_lshl_add_u64 v[182:183], v[116:117], 0, v[170:171]
	v_or_b32_e32 v116, 16, v162
	s_mov_b64 s[8:9], -1
	s_and_b64 vcc, exec, s[6:7]
	v_subrev_u32_e32 v113, s5, v116
	v_mov_b32_e32 v198, v220
	v_mov_b32_e32 v199, v221
	v_mov_b32_e32 v205, v223
	v_mov_b32_e32 v196, v224
	s_cbranch_vccz .LBB0_101
	v_ashrrev_i32_e32 v117, 31, v116
	v_lshlrev_b64 v[114:115], 6, v[116:117]
	v_lshl_add_u64 v[114:115], s[44:45], 0, v[114:115]
	v_mov_b32_e32 v161, v141
	v_lshl_add_u64 v[114:115], v[114:115], 0, v[160:161]
	flat_load_dwordx4 v[118:121], v[114:115]
	s_mov_b64 s[8:9], 0
	s_waitcnt vmcnt(0) lgkmcnt(0)
	v_mov_b32_e32 v114, v119
	v_mov_b32_e32 v115, v120
	v_mov_b32_e32 v119, v121
	v_pk_add_f32 v[114:115], v[114:115], v[118:119]
	s_nop 0
	v_add_f32_e32 v112, v114, v115
	ds_bpermute_b32 v114, v168, v112
	s_waitcnt lgkmcnt(0)
	v_add_f32_e32 v112, v112, v114
	ds_bpermute_b32 v114, v167, v112
	s_waitcnt lgkmcnt(0)
	v_add_f32_e32 v112, v112, v114
	v_fmamk_f32 v112, v112, 0x3a800000, v250
	v_rsq_f32_e32 v112, v112
	v_subrev_u32_e32 v114, s5, v116

.LBB0_103:
	s_waitcnt lgkmcnt(0)
	v_pk_mul_f32 v[106:107], v[106:107], v[112:113] op_sel_hi:[1,0]
	v_pk_mul_f32 v[104:105], v[104:105], v[112:113] op_sel_hi:[1,0]
	v_pk_mul_f32 v[110:111], v[110:111], v[112:113] op_sel_hi:[1,0]
	v_pk_mul_f32 v[108:109], v[108:109], v[112:113] op_sel_hi:[1,0]
	v_max_f32_e32 v104, 0, v104
	v_max_f32_e32 v105, 0, v105
	v_max_f32_e32 v106, 0, v106
	v_max_f32_e32 v108, 0, v108
	v_mul_f32_e32 v113, v104, v104
	v_max_f32_e32 v104, 0, v109
	v_mul_f32_e32 v109, v105, v105
	v_max_f32_e32 v105, 0, v110
	v_mul_f32_e32 v110, v106, v106
	v_max_f32_e32 v106, 0, v111
	v_mul_f32_e32 v108, v108, v108
	v_mul_f32_e32 v104, v104, v104
	v_mul_f32_e32 v105, v105, v105
	v_max_f32_e32 v107, 0, v107
	v_mul_f32_e32 v106, v106, v106
	v_ashrrev_i32_e32 v115, 31, v114
	v_mul_f32_e32 v107, v107, v107
	v_cvt_pk_bf16_f32 v104, v108, v104
	v_cvt_pk_bf16_f32 v105, v105, v106
	v_cvt_pk_bf16_f32 v106, v113, v109
	v_lshlrev_b64 v[108:109], 7, v[114:115]
	v_cvt_pk_bf16_f32 v107, v110, v107
	v_lshl_add_u64 v[110:111], s[58:59], 0, v[108:109]
	v_pk_mul_f32 v[98:99], v[98:99], v[112:113] op_sel_hi:[1,0]
	v_pk_mul_f32 v[96:97], v[96:97], v[112:113] op_sel_hi:[1,0]
	v_lshl_add_u64 v[110:111], v[110:111], 0, v[140:141]
	v_pk_mul_f32 v[102:103], v[102:103], v[112:113] op_sel_hi:[1,0]
	v_pk_mul_f32 v[100:101], v[100:101], v[112:113] op_sel_hi:[1,0]
	v_max_f32_e32 v96, 0, v96
	v_max_f32_e32 v97, 0, v97
	v_max_f32_e32 v98, 0, v98
	s_waitcnt lgkmcnt(0)
	global_store_dwordx4 v[182:183], v[178:181], off nt
	ds_bpermute_b32 v172, v169, v104
	ds_bpermute_b32 v173, v169, v105
	ds_bpermute_b32 v174, v169, v106
	ds_bpermute_b32 v175, v169, v107
	v_lshl_add_u64 v[176:177], v[110:111], 0, v[170:171]
	v_max_f32_e32 v100, 0, v100
	v_mul_f32_e32 v100, v100, v100
	v_mul_f32_e32 v104, v96, v96
	v_max_f32_e32 v96, 0, v101
	v_mul_f32_e32 v101, v97, v97
	v_max_f32_e32 v97, 0, v102
	v_mul_f32_e32 v102, v98, v98
	v_max_f32_e32 v98, 0, v103
	v_mul_f32_e32 v96, v96, v96
	v_mul_f32_e32 v97, v97, v97
	v_mul_f32_e32 v98, v98, v98
	v_max_f32_e32 v99, 0, v99
	v_cvt_pk_bf16_f32 v96, v100, v96
	v_cvt_pk_bf16_f32 v97, v97, v98
	v_cvt_pk_bf16_f32 v98, v104, v101
	v_lshl_add_u64 v[100:101], s[74:75], 0, v[108:109]
	v_mul_f32_e32 v99, v99, v99
	v_lshl_add_u64 v[100:101], v[100:101], 0, v[140:141]
	v_cvt_pk_bf16_f32 v99, v102, v99
	s_waitcnt lgkmcnt(0)
	global_store_dwordx4 v[176:177], v[172:175], off nt
	ds_bpermute_b32 v178, v169, v96
	ds_bpermute_b32 v179, v169, v97
	ds_bpermute_b32 v180, v169, v98
	ds_bpermute_b32 v181, v169, v99
	v_lshl_add_u64 v[182:183], v[100:101], 0, v[170:171]
	v_or_b32_e32 v100, 32, v162
	s_mov_b64 s[8:9], -1
	s_and_b64 vcc, exec, s[6:7]
	v_subrev_u32_e32 v97, s5, v100
	s_cbranch_vccz .LBB0_105
	v_ashrrev_i32_e32 v101, 31, v100
	v_lshlrev_b64 v[98:99], 6, v[100:101]
	v_lshl_add_u64 v[98:99], s[44:45], 0, v[98:99]
	v_mov_b32_e32 v161, v141
	v_lshl_add_u64 v[98:99], v[98:99], 0, v[160:161]
	flat_load_dwordx4 v[102:105], v[98:99]
	s_mov_b64 s[8:9], 0
	s_waitcnt vmcnt(0) lgkmcnt(0)
	v_mov_b32_e32 v98, v103
	v_mov_b32_e32 v99, v104
	v_mov_b32_e32 v103, v105
	v_pk_add_f32 v[98:99], v[98:99], v[102:103]
	s_nop 0
	v_add_f32_e32 v96, v98, v99
	ds_bpermute_b32 v98, v168, v96
	s_waitcnt lgkmcnt(0)
	v_add_f32_e32 v96, v96, v98
	ds_bpermute_b32 v98, v167, v96
	s_waitcnt lgkmcnt(0)
	v_add_f32_e32 v96, v96, v98
	v_fmamk_f32 v96, v96, 0x3a800000, v250
	v_rsq_f32_e32 v96, v96
	v_subrev_u32_e32 v98, s5, v100

.LBB0_107:
	s_waitcnt lgkmcnt(0)
	v_pk_mul_f32 v[90:91], v[90:91], v[96:97] op_sel_hi:[1,0]
	v_pk_mul_f32 v[88:89], v[88:89], v[96:97] op_sel_hi:[1,0]
	v_pk_mul_f32 v[94:95], v[94:95], v[96:97] op_sel_hi:[1,0]
	v_pk_mul_f32 v[92:93], v[92:93], v[96:97] op_sel_hi:[1,0]
	v_max_f32_e32 v88, 0, v88
	v_max_f32_e32 v89, 0, v89
	v_max_f32_e32 v90, 0, v90
	v_max_f32_e32 v92, 0, v92
	v_mul_f32_e32 v97, v88, v88
	v_max_f32_e32 v88, 0, v93
	v_mul_f32_e32 v93, v89, v89
	v_max_f32_e32 v89, 0, v94
	v_mul_f32_e32 v94, v90, v90
	v_max_f32_e32 v90, 0, v95
	v_mul_f32_e32 v92, v92, v92
	v_mul_f32_e32 v88, v88, v88
	v_mul_f32_e32 v89, v89, v89
	v_max_f32_e32 v91, 0, v91
	v_mul_f32_e32 v90, v90, v90
	v_ashrrev_i32_e32 v99, 31, v98
	v_mul_f32_e32 v91, v91, v91
	v_cvt_pk_bf16_f32 v88, v92, v88
	v_cvt_pk_bf16_f32 v89, v89, v90
	v_cvt_pk_bf16_f32 v90, v97, v93
	v_lshlrev_b64 v[92:93], 7, v[98:99]
	v_cvt_pk_bf16_f32 v91, v94, v91
	v_lshl_add_u64 v[94:95], s[58:59], 0, v[92:93]
	v_pk_mul_f32 v[82:83], v[82:83], v[96:97] op_sel_hi:[1,0]
	v_pk_mul_f32 v[80:81], v[80:81], v[96:97] op_sel_hi:[1,0]
	v_lshl_add_u64 v[94:95], v[94:95], 0, v[140:141]
	v_pk_mul_f32 v[86:87], v[86:87], v[96:97] op_sel_hi:[1,0]
	v_pk_mul_f32 v[84:85], v[84:85], v[96:97] op_sel_hi:[1,0]
	v_max_f32_e32 v80, 0, v80
	v_max_f32_e32 v81, 0, v81
	v_max_f32_e32 v82, 0, v82
	s_waitcnt lgkmcnt(0)
	global_store_dwordx4 v[182:183], v[178:181], off nt
	ds_bpermute_b32 v172, v169, v88
	ds_bpermute_b32 v173, v169, v89
	ds_bpermute_b32 v174, v169, v90
	ds_bpermute_b32 v175, v169, v91
	v_lshl_add_u64 v[176:177], v[94:95], 0, v[170:171]
	v_max_f32_e32 v84, 0, v84
	v_mul_f32_e32 v84, v84, v84
	v_mul_f32_e32 v88, v80, v80
	v_max_f32_e32 v80, 0, v85
	v_mul_f32_e32 v85, v81, v81
	v_max_f32_e32 v81, 0, v86
	v_mul_f32_e32 v86, v82, v82
	v_max_f32_e32 v82, 0, v87
	v_mul_f32_e32 v80, v80, v80
	v_mul_f32_e32 v81, v81, v81
	v_mul_f32_e32 v82, v82, v82
	v_max_f32_e32 v83, 0, v83
	v_cvt_pk_bf16_f32 v80, v84, v80
	v_cvt_pk_bf16_f32 v81, v81, v82
	v_cvt_pk_bf16_f32 v82, v88, v85
	v_lshl_add_u64 v[84:85], s[74:75], 0, v[92:93]
	v_mul_f32_e32 v83, v83, v83
	v_lshl_add_u64 v[84:85], v[84:85], 0, v[140:141]
	v_cvt_pk_bf16_f32 v83, v86, v83
	s_waitcnt lgkmcnt(0)
	global_store_dwordx4 v[176:177], v[172:175], off nt
	ds_bpermute_b32 v178, v169, v80
	ds_bpermute_b32 v179, v169, v81
	ds_bpermute_b32 v180, v169, v82
	ds_bpermute_b32 v181, v169, v83
	v_lshl_add_u64 v[182:183], v[84:85], 0, v[170:171]
	v_or_b32_e32 v84, 48, v162
	s_mov_b64 s[8:9], -1
	s_and_b64 vcc, exec, s[6:7]
	v_subrev_u32_e32 v81, s5, v84
	s_cbranch_vccz .LBB0_109
	v_ashrrev_i32_e32 v85, 31, v84
	v_lshlrev_b64 v[82:83], 6, v[84:85]
	v_lshl_add_u64 v[82:83], s[44:45], 0, v[82:83]
	v_mov_b32_e32 v161, v141
	v_lshl_add_u64 v[82:83], v[82:83], 0, v[160:161]
	flat_load_dwordx4 v[86:89], v[82:83]
	s_mov_b64 s[8:9], 0
	s_waitcnt vmcnt(0) lgkmcnt(0)
	v_mov_b32_e32 v82, v87
	v_mov_b32_e32 v83, v88
	v_mov_b32_e32 v87, v89
	v_pk_add_f32 v[82:83], v[82:83], v[86:87]
	s_nop 0
	v_add_f32_e32 v80, v82, v83
	ds_bpermute_b32 v82, v168, v80
	s_waitcnt lgkmcnt(0)
	v_add_f32_e32 v80, v80, v82
	ds_bpermute_b32 v82, v167, v80
	s_waitcnt lgkmcnt(0)
	v_add_f32_e32 v80, v80, v82
	v_fmamk_f32 v80, v80, 0x3a800000, v250
	v_rsq_f32_e32 v80, v80
	v_subrev_u32_e32 v82, s5, v84

.LBB0_111:
	s_waitcnt lgkmcnt(0)
	v_pk_mul_f32 v[74:75], v[74:75], v[80:81] op_sel_hi:[1,0]
	v_pk_mul_f32 v[72:73], v[72:73], v[80:81] op_sel_hi:[1,0]
	v_pk_mul_f32 v[78:79], v[78:79], v[80:81] op_sel_hi:[1,0]
	v_pk_mul_f32 v[76:77], v[76:77], v[80:81] op_sel_hi:[1,0]
	v_max_f32_e32 v72, 0, v72
	v_max_f32_e32 v73, 0, v73
	v_max_f32_e32 v74, 0, v74
	v_max_f32_e32 v76, 0, v76
	v_mul_f32_e32 v81, v72, v72
	v_max_f32_e32 v72, 0, v77
	v_mul_f32_e32 v77, v73, v73
	v_max_f32_e32 v73, 0, v78
	v_mul_f32_e32 v78, v74, v74
	v_max_f32_e32 v74, 0, v79
	v_mul_f32_e32 v76, v76, v76
	v_mul_f32_e32 v72, v72, v72
	v_mul_f32_e32 v73, v73, v73
	v_max_f32_e32 v75, 0, v75
	v_mul_f32_e32 v74, v74, v74
	v_ashrrev_i32_e32 v83, 31, v82
	v_mul_f32_e32 v75, v75, v75
	v_cvt_pk_bf16_f32 v72, v76, v72
	v_cvt_pk_bf16_f32 v73, v73, v74
	v_cvt_pk_bf16_f32 v74, v81, v77
	v_lshlrev_b64 v[76:77], 7, v[82:83]
	v_cvt_pk_bf16_f32 v75, v78, v75
	v_lshl_add_u64 v[78:79], s[58:59], 0, v[76:77]
	v_pk_mul_f32 v[66:67], v[66:67], v[80:81] op_sel_hi:[1,0]
	v_pk_mul_f32 v[64:65], v[64:65], v[80:81] op_sel_hi:[1,0]
	v_lshl_add_u64 v[78:79], v[78:79], 0, v[140:141]
	v_pk_mul_f32 v[70:71], v[70:71], v[80:81] op_sel_hi:[1,0]
	v_pk_mul_f32 v[68:69], v[68:69], v[80:81] op_sel_hi:[1,0]
	v_max_f32_e32 v64, 0, v64
	v_max_f32_e32 v65, 0, v65
	v_max_f32_e32 v66, 0, v66
	s_waitcnt lgkmcnt(0)
	global_store_dwordx4 v[182:183], v[178:181], off nt
	ds_bpermute_b32 v172, v169, v72
	ds_bpermute_b32 v173, v169, v73
	ds_bpermute_b32 v174, v169, v74
	ds_bpermute_b32 v175, v169, v75
	v_lshl_add_u64 v[176:177], v[78:79], 0, v[170:171]
	v_max_f32_e32 v68, 0, v68
	v_mul_f32_e32 v68, v68, v68
	v_mul_f32_e32 v72, v64, v64
	v_max_f32_e32 v64, 0, v69
	v_mul_f32_e32 v69, v65, v65
	v_max_f32_e32 v65, 0, v70
	v_mul_f32_e32 v70, v66, v66
	v_max_f32_e32 v66, 0, v71
	v_mul_f32_e32 v64, v64, v64
	v_mul_f32_e32 v65, v65, v65
	v_mul_f32_e32 v66, v66, v66
	v_max_f32_e32 v67, 0, v67
	v_cvt_pk_bf16_f32 v64, v68, v64
	v_cvt_pk_bf16_f32 v65, v65, v66
	v_cvt_pk_bf16_f32 v66, v72, v69
	v_lshl_add_u64 v[68:69], s[74:75], 0, v[76:77]
	v_mul_f32_e32 v67, v67, v67
	v_lshl_add_u64 v[68:69], v[68:69], 0, v[140:141]
	v_cvt_pk_bf16_f32 v67, v70, v67
	s_waitcnt lgkmcnt(0)
	global_store_dwordx4 v[176:177], v[172:175], off nt
	ds_bpermute_b32 v178, v169, v64
	ds_bpermute_b32 v179, v169, v65
	ds_bpermute_b32 v180, v169, v66
	ds_bpermute_b32 v181, v169, v67
	v_lshl_add_u64 v[182:183], v[68:69], 0, v[170:171]
	v_add_u32_e32 v68, 0x80, v162
	s_mov_b64 s[8:9], -1
	s_and_b64 vcc, exec, s[6:7]
	v_subrev_u32_e32 v65, s5, v68
	s_cbranch_vccz .LBB0_113
	v_ashrrev_i32_e32 v69, 31, v68
	v_lshlrev_b64 v[66:67], 6, v[68:69]
	v_lshl_add_u64 v[66:67], s[44:45], 0, v[66:67]
	v_mov_b32_e32 v161, v141
	v_lshl_add_u64 v[66:67], v[66:67], 0, v[160:161]
	flat_load_dwordx4 v[70:73], v[66:67]
	s_mov_b64 s[8:9], 0
	s_waitcnt vmcnt(0) lgkmcnt(0)
	v_mov_b32_e32 v66, v71
	v_mov_b32_e32 v67, v72
	v_mov_b32_e32 v71, v73
	v_pk_add_f32 v[66:67], v[66:67], v[70:71]
	s_nop 0
	v_add_f32_e32 v64, v66, v67
	ds_bpermute_b32 v66, v168, v64
	s_waitcnt lgkmcnt(0)
	v_add_f32_e32 v64, v64, v66
	ds_bpermute_b32 v66, v167, v64
	s_waitcnt lgkmcnt(0)
	v_add_f32_e32 v64, v64, v66
	v_fmamk_f32 v64, v64, 0x3a800000, v250
	v_rsq_f32_e32 v64, v64
	v_subrev_u32_e32 v66, s5, v68

.LBB0_115:
	s_waitcnt lgkmcnt(0)
	v_pk_mul_f32 v[58:59], v[58:59], v[64:65] op_sel_hi:[1,0]
	v_pk_mul_f32 v[56:57], v[56:57], v[64:65] op_sel_hi:[1,0]
	v_pk_mul_f32 v[62:63], v[62:63], v[64:65] op_sel_hi:[1,0]
	v_pk_mul_f32 v[60:61], v[60:61], v[64:65] op_sel_hi:[1,0]
	v_max_f32_e32 v56, 0, v56
	v_max_f32_e32 v57, 0, v57
	v_max_f32_e32 v58, 0, v58
	v_max_f32_e32 v60, 0, v60
	v_mul_f32_e32 v65, v56, v56
	v_max_f32_e32 v56, 0, v61
	v_mul_f32_e32 v61, v57, v57
	v_max_f32_e32 v57, 0, v62
	v_mul_f32_e32 v62, v58, v58
	v_max_f32_e32 v58, 0, v63
	v_mul_f32_e32 v60, v60, v60
	v_mul_f32_e32 v56, v56, v56
	v_mul_f32_e32 v57, v57, v57
	v_max_f32_e32 v59, 0, v59
	v_mul_f32_e32 v58, v58, v58
	v_ashrrev_i32_e32 v67, 31, v66
	v_mul_f32_e32 v59, v59, v59
	v_cvt_pk_bf16_f32 v56, v60, v56
	v_cvt_pk_bf16_f32 v57, v57, v58
	v_cvt_pk_bf16_f32 v58, v65, v61
	v_lshlrev_b64 v[60:61], 7, v[66:67]
	v_cvt_pk_bf16_f32 v59, v62, v59
	v_lshl_add_u64 v[62:63], s[58:59], 0, v[60:61]
	v_pk_mul_f32 v[50:51], v[50:51], v[64:65] op_sel_hi:[1,0]
	v_pk_mul_f32 v[48:49], v[48:49], v[64:65] op_sel_hi:[1,0]
	v_lshl_add_u64 v[62:63], v[62:63], 0, v[140:141]
	v_pk_mul_f32 v[54:55], v[54:55], v[64:65] op_sel_hi:[1,0]
	v_pk_mul_f32 v[52:53], v[52:53], v[64:65] op_sel_hi:[1,0]
	v_max_f32_e32 v48, 0, v48
	v_max_f32_e32 v49, 0, v49
	v_max_f32_e32 v50, 0, v50
	s_waitcnt lgkmcnt(0)
	global_store_dwordx4 v[182:183], v[178:181], off nt
	ds_bpermute_b32 v172, v169, v56
	ds_bpermute_b32 v173, v169, v57
	ds_bpermute_b32 v174, v169, v58
	ds_bpermute_b32 v175, v169, v59
	v_lshl_add_u64 v[176:177], v[62:63], 0, v[170:171]
	v_max_f32_e32 v52, 0, v52
	v_mul_f32_e32 v52, v52, v52
	v_mul_f32_e32 v56, v48, v48
	v_max_f32_e32 v48, 0, v53
	v_mul_f32_e32 v53, v49, v49
	v_max_f32_e32 v49, 0, v54
	v_mul_f32_e32 v54, v50, v50
	v_max_f32_e32 v50, 0, v55
	v_mul_f32_e32 v48, v48, v48
	v_mul_f32_e32 v49, v49, v49
	v_mul_f32_e32 v50, v50, v50
	v_max_f32_e32 v51, 0, v51
	v_cvt_pk_bf16_f32 v48, v52, v48
	v_cvt_pk_bf16_f32 v49, v49, v50
	v_cvt_pk_bf16_f32 v50, v56, v53
	v_lshl_add_u64 v[52:53], s[74:75], 0, v[60:61]
	v_mul_f32_e32 v51, v51, v51
	v_lshl_add_u64 v[52:53], v[52:53], 0, v[140:141]
	v_cvt_pk_bf16_f32 v51, v54, v51
	s_waitcnt lgkmcnt(0)
	global_store_dwordx4 v[176:177], v[172:175], off nt
	ds_bpermute_b32 v178, v169, v48
	ds_bpermute_b32 v179, v169, v49
	ds_bpermute_b32 v180, v169, v50
	ds_bpermute_b32 v181, v169, v51
	v_lshl_add_u64 v[182:183], v[52:53], 0, v[170:171]
	v_add_u32_e32 v52, 0x90, v162
	s_mov_b64 s[8:9], -1
	s_and_b64 vcc, exec, s[6:7]
	v_subrev_u32_e32 v49, s5, v52
	s_cbranch_vccz .LBB0_117
	v_ashrrev_i32_e32 v53, 31, v52
	v_lshlrev_b64 v[50:51], 6, v[52:53]
	v_lshl_add_u64 v[50:51], s[44:45], 0, v[50:51]
	v_mov_b32_e32 v161, v141
	v_lshl_add_u64 v[50:51], v[50:51], 0, v[160:161]
	flat_load_dwordx4 v[54:57], v[50:51]
	s_mov_b64 s[8:9], 0
	s_waitcnt vmcnt(0) lgkmcnt(0)
	v_mov_b32_e32 v50, v55
	v_mov_b32_e32 v51, v56
	v_mov_b32_e32 v55, v57
	v_pk_add_f32 v[50:51], v[50:51], v[54:55]
	s_nop 0
	v_add_f32_e32 v48, v50, v51
	ds_bpermute_b32 v50, v168, v48
	s_waitcnt lgkmcnt(0)
	v_add_f32_e32 v48, v48, v50
	ds_bpermute_b32 v50, v167, v48
	s_waitcnt lgkmcnt(0)
	v_add_f32_e32 v48, v48, v50
	v_fmamk_f32 v48, v48, 0x3a800000, v250
	v_rsq_f32_e32 v48, v48
	v_subrev_u32_e32 v50, s5, v52

.LBB0_119:
	s_waitcnt lgkmcnt(0)
	v_pk_mul_f32 v[42:43], v[42:43], v[48:49] op_sel_hi:[1,0]
	v_pk_mul_f32 v[40:41], v[40:41], v[48:49] op_sel_hi:[1,0]
	v_pk_mul_f32 v[46:47], v[46:47], v[48:49] op_sel_hi:[1,0]
	v_pk_mul_f32 v[44:45], v[44:45], v[48:49] op_sel_hi:[1,0]
	v_max_f32_e32 v40, 0, v40
	v_max_f32_e32 v41, 0, v41
	v_max_f32_e32 v42, 0, v42
	v_max_f32_e32 v44, 0, v44
	v_mul_f32_e32 v49, v40, v40
	v_max_f32_e32 v40, 0, v45
	v_mul_f32_e32 v45, v41, v41
	v_max_f32_e32 v41, 0, v46
	v_mul_f32_e32 v46, v42, v42
	v_max_f32_e32 v42, 0, v47
	v_mul_f32_e32 v44, v44, v44
	v_mul_f32_e32 v40, v40, v40
	v_mul_f32_e32 v41, v41, v41
	v_max_f32_e32 v43, 0, v43
	v_mul_f32_e32 v42, v42, v42
	v_ashrrev_i32_e32 v51, 31, v50
	v_mul_f32_e32 v43, v43, v43
	v_cvt_pk_bf16_f32 v40, v44, v40
	v_cvt_pk_bf16_f32 v41, v41, v42
	v_cvt_pk_bf16_f32 v42, v49, v45
	v_lshlrev_b64 v[44:45], 7, v[50:51]
	v_cvt_pk_bf16_f32 v43, v46, v43
	v_lshl_add_u64 v[46:47], s[58:59], 0, v[44:45]
	v_pk_mul_f32 v[34:35], v[34:35], v[48:49] op_sel_hi:[1,0]
	v_pk_mul_f32 v[32:33], v[32:33], v[48:49] op_sel_hi:[1,0]
	v_lshl_add_u64 v[46:47], v[46:47], 0, v[140:141]
	v_pk_mul_f32 v[38:39], v[38:39], v[48:49] op_sel_hi:[1,0]
	v_pk_mul_f32 v[36:37], v[36:37], v[48:49] op_sel_hi:[1,0]
	v_max_f32_e32 v32, 0, v32
	v_max_f32_e32 v33, 0, v33
	v_max_f32_e32 v34, 0, v34
	s_waitcnt lgkmcnt(0)
	global_store_dwordx4 v[182:183], v[178:181], off nt
	ds_bpermute_b32 v172, v169, v40
	ds_bpermute_b32 v173, v169, v41
	ds_bpermute_b32 v174, v169, v42
	ds_bpermute_b32 v175, v169, v43
	v_lshl_add_u64 v[176:177], v[46:47], 0, v[170:171]
	v_max_f32_e32 v36, 0, v36
	v_mul_f32_e32 v36, v36, v36
	v_mul_f32_e32 v40, v32, v32
	v_max_f32_e32 v32, 0, v37
	v_mul_f32_e32 v37, v33, v33
	v_max_f32_e32 v33, 0, v38
	v_mul_f32_e32 v38, v34, v34
	v_max_f32_e32 v34, 0, v39
	v_mul_f32_e32 v32, v32, v32
	v_mul_f32_e32 v33, v33, v33
	v_mul_f32_e32 v34, v34, v34
	v_max_f32_e32 v35, 0, v35
	v_cvt_pk_bf16_f32 v32, v36, v32
	v_cvt_pk_bf16_f32 v33, v33, v34
	v_cvt_pk_bf16_f32 v34, v40, v37
	v_lshl_add_u64 v[36:37], s[74:75], 0, v[44:45]
	v_mul_f32_e32 v35, v35, v35
	v_lshl_add_u64 v[36:37], v[36:37], 0, v[140:141]
	v_cvt_pk_bf16_f32 v35, v38, v35
	s_waitcnt lgkmcnt(0)
	global_store_dwordx4 v[176:177], v[172:175], off nt
	ds_bpermute_b32 v178, v169, v32
	ds_bpermute_b32 v179, v169, v33
	ds_bpermute_b32 v180, v169, v34
	ds_bpermute_b32 v181, v169, v35
	v_lshl_add_u64 v[182:183], v[36:37], 0, v[170:171]
	v_add_u32_e32 v36, 0xa0, v162
	s_mov_b64 s[8:9], -1
	s_and_b64 vcc, exec, s[6:7]
	v_subrev_u32_e32 v33, s5, v36
	s_cbranch_vccz .LBB0_121
	v_ashrrev_i32_e32 v37, 31, v36
	v_lshlrev_b64 v[34:35], 6, v[36:37]
	v_lshl_add_u64 v[34:35], s[44:45], 0, v[34:35]
	v_mov_b32_e32 v161, v141
	v_lshl_add_u64 v[34:35], v[34:35], 0, v[160:161]
	flat_load_dwordx4 v[38:41], v[34:35]
	s_mov_b64 s[8:9], 0
	s_waitcnt vmcnt(0) lgkmcnt(0)
	v_mov_b32_e32 v34, v39
	v_mov_b32_e32 v35, v40
	v_mov_b32_e32 v39, v41
	v_pk_add_f32 v[34:35], v[34:35], v[38:39]
	s_nop 0
	v_add_f32_e32 v32, v34, v35
	ds_bpermute_b32 v34, v168, v32
	s_waitcnt lgkmcnt(0)
	v_add_f32_e32 v32, v32, v34
	ds_bpermute_b32 v34, v167, v32
	s_waitcnt lgkmcnt(0)
	v_add_f32_e32 v32, v32, v34
	v_fmamk_f32 v32, v32, 0x3a800000, v250
	v_rsq_f32_e32 v32, v32
	v_subrev_u32_e32 v34, s5, v36

.LBB0_123:
	s_waitcnt lgkmcnt(0)
	v_pk_mul_f32 v[26:27], v[26:27], v[32:33] op_sel_hi:[1,0]
	v_pk_mul_f32 v[24:25], v[24:25], v[32:33] op_sel_hi:[1,0]
	v_pk_mul_f32 v[30:31], v[30:31], v[32:33] op_sel_hi:[1,0]
	v_pk_mul_f32 v[28:29], v[28:29], v[32:33] op_sel_hi:[1,0]
	v_max_f32_e32 v24, 0, v24
	v_max_f32_e32 v25, 0, v25
	v_max_f32_e32 v26, 0, v26
	v_max_f32_e32 v28, 0, v28
	v_mul_f32_e32 v33, v24, v24
	v_max_f32_e32 v24, 0, v29
	v_mul_f32_e32 v29, v25, v25
	v_max_f32_e32 v25, 0, v30
	v_mul_f32_e32 v30, v26, v26
	v_max_f32_e32 v26, 0, v31
	v_mul_f32_e32 v28, v28, v28
	v_mul_f32_e32 v24, v24, v24
	v_mul_f32_e32 v25, v25, v25
	v_max_f32_e32 v27, 0, v27
	v_mul_f32_e32 v26, v26, v26
	v_ashrrev_i32_e32 v35, 31, v34
	v_mul_f32_e32 v27, v27, v27
	v_cvt_pk_bf16_f32 v24, v28, v24
	v_cvt_pk_bf16_f32 v25, v25, v26
	v_cvt_pk_bf16_f32 v26, v33, v29
	v_lshlrev_b64 v[28:29], 7, v[34:35]
	v_cvt_pk_bf16_f32 v27, v30, v27
	v_lshl_add_u64 v[30:31], s[58:59], 0, v[28:29]
	v_pk_mul_f32 v[18:19], v[18:19], v[32:33] op_sel_hi:[1,0]
	v_pk_mul_f32 v[16:17], v[16:17], v[32:33] op_sel_hi:[1,0]
	v_lshl_add_u64 v[30:31], v[30:31], 0, v[140:141]
	v_pk_mul_f32 v[22:23], v[22:23], v[32:33] op_sel_hi:[1,0]
	v_pk_mul_f32 v[20:21], v[20:21], v[32:33] op_sel_hi:[1,0]
	v_max_f32_e32 v16, 0, v16
	v_max_f32_e32 v17, 0, v17
	v_max_f32_e32 v18, 0, v18
	s_waitcnt lgkmcnt(0)
	global_store_dwordx4 v[182:183], v[178:181], off nt
	ds_bpermute_b32 v172, v169, v24
	ds_bpermute_b32 v173, v169, v25
	ds_bpermute_b32 v174, v169, v26
	ds_bpermute_b32 v175, v169, v27
	v_lshl_add_u64 v[176:177], v[30:31], 0, v[170:171]
	v_max_f32_e32 v20, 0, v20
	v_mul_f32_e32 v20, v20, v20
	v_mul_f32_e32 v24, v16, v16
	v_max_f32_e32 v16, 0, v21
	v_mul_f32_e32 v21, v17, v17
	v_max_f32_e32 v17, 0, v22
	v_mul_f32_e32 v22, v18, v18
	v_max_f32_e32 v18, 0, v23
	v_mul_f32_e32 v16, v16, v16
	v_mul_f32_e32 v17, v17, v17
	v_mul_f32_e32 v18, v18, v18
	v_max_f32_e32 v19, 0, v19
	v_cvt_pk_bf16_f32 v16, v20, v16
	v_cvt_pk_bf16_f32 v17, v17, v18
	v_cvt_pk_bf16_f32 v18, v24, v21
	v_lshl_add_u64 v[20:21], s[74:75], 0, v[28:29]
	v_mul_f32_e32 v19, v19, v19
	v_lshl_add_u64 v[20:21], v[20:21], 0, v[140:141]
	v_cvt_pk_bf16_f32 v19, v22, v19
	s_waitcnt lgkmcnt(0)
	global_store_dwordx4 v[176:177], v[172:175], off nt
	ds_bpermute_b32 v178, v169, v16
	ds_bpermute_b32 v179, v169, v17
	ds_bpermute_b32 v180, v169, v18
	ds_bpermute_b32 v181, v169, v19
	v_lshl_add_u64 v[182:183], v[20:21], 0, v[170:171]
	v_add_u32_e32 v20, 0xb0, v162
	s_mov_b64 s[8:9], -1
	s_and_b64 vcc, exec, s[6:7]
	v_subrev_u32_e32 v17, s5, v20
	s_cbranch_vccz .LBB0_125
	v_ashrrev_i32_e32 v21, 31, v20
	v_lshlrev_b64 v[18:19], 6, v[20:21]
	v_lshl_add_u64 v[18:19], s[44:45], 0, v[18:19]
	v_mov_b32_e32 v161, v141
	v_lshl_add_u64 v[18:19], v[18:19], 0, v[160:161]
	flat_load_dwordx4 v[22:25], v[18:19]
	s_mov_b64 s[8:9], 0
	s_waitcnt vmcnt(0) lgkmcnt(0)
	v_mov_b32_e32 v18, v23
	v_mov_b32_e32 v19, v24
	v_mov_b32_e32 v23, v25
	v_pk_add_f32 v[18:19], v[18:19], v[22:23]
	s_nop 0
	v_add_f32_e32 v16, v18, v19
	ds_bpermute_b32 v18, v168, v16
	s_waitcnt lgkmcnt(0)
	v_add_f32_e32 v16, v16, v18
	ds_bpermute_b32 v18, v167, v16
	s_waitcnt lgkmcnt(0)
	v_add_f32_e32 v16, v16, v18
	v_fmamk_f32 v16, v16, 0x3a800000, v250
	v_rsq_f32_e32 v16, v16
	v_subrev_u32_e32 v18, s5, v20

.LBB0_127:
	s_waitcnt lgkmcnt(0)
	v_pk_mul_f32 v[10:11], v[10:11], v[16:17] op_sel_hi:[1,0]
	v_pk_mul_f32 v[8:9], v[8:9], v[16:17] op_sel_hi:[1,0]
	v_pk_mul_f32 v[14:15], v[14:15], v[16:17] op_sel_hi:[1,0]
	v_pk_mul_f32 v[12:13], v[12:13], v[16:17] op_sel_hi:[1,0]
	v_max_f32_e32 v8, 0, v8
	v_max_f32_e32 v9, 0, v9
	v_max_f32_e32 v10, 0, v10
	v_max_f32_e32 v12, 0, v12
	v_mul_f32_e32 v17, v8, v8
	v_max_f32_e32 v8, 0, v13
	v_mul_f32_e32 v13, v9, v9
	v_max_f32_e32 v9, 0, v14
	v_mul_f32_e32 v14, v10, v10
	v_max_f32_e32 v10, 0, v15
	v_mul_f32_e32 v12, v12, v12
	v_mul_f32_e32 v8, v8, v8
	v_mul_f32_e32 v9, v9, v9
	v_max_f32_e32 v11, 0, v11
	v_mul_f32_e32 v10, v10, v10
	v_ashrrev_i32_e32 v19, 31, v18
	v_mul_f32_e32 v11, v11, v11
	v_cvt_pk_bf16_f32 v8, v12, v8
	v_cvt_pk_bf16_f32 v9, v9, v10
	v_cvt_pk_bf16_f32 v10, v17, v13
	v_lshlrev_b64 v[12:13], 7, v[18:19]
	v_cvt_pk_bf16_f32 v11, v14, v11
	v_lshl_add_u64 v[14:15], s[58:59], 0, v[12:13]
	v_pk_mul_f32 v[2:3], v[2:3], v[16:17] op_sel_hi:[1,0]
	v_pk_mul_f32 v[0:1], v[0:1], v[16:17] op_sel_hi:[1,0]
	v_lshl_add_u64 v[14:15], v[14:15], 0, v[140:141]
	v_pk_mul_f32 v[6:7], v[6:7], v[16:17] op_sel_hi:[1,0]
	v_pk_mul_f32 v[4:5], v[4:5], v[16:17] op_sel_hi:[1,0]
	v_max_f32_e32 v0, 0, v0
	v_max_f32_e32 v1, 0, v1
	v_max_f32_e32 v2, 0, v2
	s_waitcnt lgkmcnt(0)
	global_store_dwordx4 v[182:183], v[178:181], off nt
	ds_bpermute_b32 v172, v169, v8
	ds_bpermute_b32 v173, v169, v9
	ds_bpermute_b32 v174, v169, v10
	ds_bpermute_b32 v175, v169, v11
	v_lshl_add_u64 v[176:177], v[14:15], 0, v[170:171]
	v_max_f32_e32 v4, 0, v4
	v_mul_f32_e32 v4, v4, v4
	v_mul_f32_e32 v8, v0, v0
	v_max_f32_e32 v0, 0, v5
	v_mul_f32_e32 v5, v1, v1
	v_max_f32_e32 v1, 0, v6
	v_mul_f32_e32 v6, v2, v2
	v_max_f32_e32 v2, 0, v7
	v_mul_f32_e32 v0, v0, v0
	v_mul_f32_e32 v1, v1, v1
	v_mul_f32_e32 v2, v2, v2
	v_max_f32_e32 v3, 0, v3
	v_cvt_pk_bf16_f32 v0, v4, v0
	v_cvt_pk_bf16_f32 v1, v1, v2
	v_cvt_pk_bf16_f32 v2, v8, v5
	v_lshl_add_u64 v[4:5], s[74:75], 0, v[12:13]
	v_mul_f32_e32 v3, v3, v3
	v_lshl_add_u64 v[4:5], v[4:5], 0, v[140:141]
	s_andn2_b64 vcc, exec, s[40:41]
	s_mov_b64 s[6:7], -1
	v_cvt_pk_bf16_f32 v3, v6, v3
	s_waitcnt lgkmcnt(0)
	global_store_dwordx4 v[176:177], v[172:175], off nt
	ds_bpermute_b32 v178, v169, v0
	ds_bpermute_b32 v179, v169, v1
	ds_bpermute_b32 v180, v169, v2
	ds_bpermute_b32 v181, v169, v3
	v_lshl_add_u64 v[182:183], v[4:5], 0, v[170:171]
	s_waitcnt lgkmcnt(0)
	global_store_dwordx4 v[182:183], v[178:181], off nt
	s_cbranch_vccnz .LBB0_84
	s_cmp_lg_u32 s52, s46
	s_cselect_b64 s[4:5], -1, 0
	s_and_b64 s[4:5], s[40:41], s[4:5]
	v_cndmask_b32_e64 v0, 0, 1, s[4:5]
	s_andn2_b64 vcc, exec, s[2:3]
	v_readfirstlane_b32 s4, v0
	s_cbranch_vccnz .LBB0_83
	s_barrier
	s_branch .LBB0_83
